# standalone rms_rows phases: next row prefetched while the current row is reduced and stored (counted vmcnt, stores not waited on)
# speedup vs baseline: 1.0021x; 1.0021x over previous
;     static __device__ __forceinline__ float gv(unsigned long long gw, int i) { return __uint_as_float((unsigned)((gw >> (16 * i)) & 0xffffull) << 16); }
; __device__ __forceinline__ float opq(float v) { asm volatile("" : "+v"(v)); return v; }
; #define GET_IDS() unsigned zz_ = 0u; asm volatile("" : "+v"(zz_)); int lane = (int)__builtin_amdgcn_mbcnt_hi(~0u, __builtin_amdgcn_mbcnt_lo(~0u, zz_)); int wave = wave_id; asm volatile("" : "+s"(wave)); int tid = wave * 64 + lane; const int gw = bid * 8 + wave, gwb = wave * G + bid; (void)gw; (void)gwb; (void)lane
; __device__ __forceinline__ void rms_rows(const float* x, const float* gain, bf16_t* out, int nrows, int gw, int NGW, int lane) {
;     f32x4 gv[4];
; #pragma unroll
;     for (int j = 0; j < 4; ++j) gv[j] = *((const f32x4*)gain + lane + 64 * j);
;     for (int m = gw; m < nrows; m += NGW) {
;         const f32x4* xr = (const f32x4*)(x + (size_t)m * DM) + lane; f32x4 v[4]; float ss = 0.f;
; #pragma unroll
;         for (int j = 0; j < 4; ++j) { v[j] = xr[64 * j]; ss += (v[j].x * v[j].x + v[j].y * v[j].y) + (v[j].z * v[j].z + v[j].w * v[j].w); }
;         const float rstd = rsqrtf(wave_sum(ss, lane) * (1.f / DM) + opq(EPS));
;         u32x2* o = (u32x2*)(out + (size_t)m * DM) + lane;
; __global__ void __launch_bounds__(512, 2) mega_fwd(Args A_) {
;     ...
;             } else if (st == 18) {
;                 GET_IDS();
;                 rms_rows(A.out() + (size_t)TG * DM, A.in(I_F2N) + L * DM, hbuf + (size_t)TG * DM, TG, gw, NGW, lane);
.LBB0_651:
	s_and_b64 vcc, exec, s[6:7]
	s_cbranch_vccz .LBB0_1019
	s_mov_b64 s[6:7], -1
	s_mov_b64 s[2:3], 0
	s_cmp_lt_i32 s60, 18
	s_mov_b64 s[4:5], 0
	s_cbranch_scc1 .LBB0_664
	s_cmp_eq_u32 s60, 18
	s_mov_b64 s[4:5], -1
	s_cbranch_scc0 .LBB0_658
	v_mov_b32_e32 v0, v1
	v_readlane_b32 s0, v254, 5
	s_lshl_b32 s1, s79, 3
	s_add_i32 s4, s0, s1
	v_readlane_b32 s0, v254, 30
	v_readlane_b32 s10, v254, 19
	s_cmpk_gt_i32 s4, 0x1fff
	v_readlane_b32 s1, v254, 31
	v_readlane_b32 s11, v254, 20
	s_cbranch_scc1 .LBB0_657
	v_readlane_b32 s12, v254, 36
	v_readlane_b32 s13, v254, 37
	s_load_dwordx2 s[6:7], s[12:13], 0xc0
	v_readlane_b32 s8, v254, 32
	v_readlane_b32 s9, v254, 33
	s_lshl_b32 s8, s8, 10
	v_mbcnt_lo_u32_b32 v0, -1, v0
	s_ashr_i32 s9, s8, 31
	s_lshl_b64 s[8:9], s[8:9], 2
	v_mbcnt_hi_u32_b32 v20, -1, v0
	s_waitcnt lgkmcnt(0)
	s_add_u32 s6, s6, s8
	v_ashrrev_i32_e32 v21, 31, v20
	s_addc_u32 s7, s7, s9
	v_lshlrev_b64 v[18:19], 4, v[20:21]
	v_lshl_add_u64 v[14:15], s[6:7], 0, v[18:19]
	global_load_dwordx4 v[2:5], v[14:15], off offset:3072
	global_load_dwordx4 v[6:9], v[14:15], off offset:2048
	global_load_dwordx4 v[10:13], v[14:15], off offset:1024
	s_nop 0
	global_load_dwordx4 v[14:17], v[14:15], off
	s_load_dwordx2 s[6:7], s[12:13], 0xd8
	s_ashr_i32 s5, s4, 31
	s_lshl_b64 s[8:9], s[4:5], 12
	v_lshlrev_b32_e32 v25, 2, v20
	v_xor_b32_e32 v0, 4, v25
	s_waitcnt lgkmcnt(0)
	s_add_u32 s6, s6, s8
	s_addc_u32 s7, s7, s9
	v_lshl_add_u64 v[18:19], s[6:7], 0, v[18:19]
	s_mov_b64 s[6:7], 0x2000000
	v_lshl_add_u64 v[18:19], v[18:19], 0, s[6:7]
	s_lshl_b64 s[6:7], s[4:5], 11
	s_add_u32 s6, s90, s6
	s_addc_u32 s7, s91, s7
	v_lshl_add_u64 v[20:21], v[20:21], 3, s[6:7]
	s_mov_b64 s[6:7], 0x4800000
	v_xor_b32_e32 v22, 8, v25
	v_xor_b32_e32 v23, 16, v25
	v_xor_b32_e32 v24, 32, v25
	v_xor_b32_e32 v25, 64, v25
	v_lshl_add_u64 v[20:21], v[20:21], 0, s[6:7]
	global_load_dwordx4 v[60:63], v[18:19], off
	global_load_dwordx4 v[64:67], v[18:19], off offset:1024
	global_load_dwordx4 v[68:71], v[18:19], off offset:2048
	global_load_dwordx4 v[72:75], v[18:19], off offset:3072
	s_waitcnt vmcnt(0)
	s_branch .Lrmsp656_body

;     static __device__ __forceinline__ float gv(unsigned long long gw, int i) { return __uint_as_float((unsigned)((gw >> (16 * i)) & 0xffffull) << 16); }
; __device__ __forceinline__ float opq(float v) { asm volatile("" : "+v"(v)); return v; }
; __device__ __forceinline__ unsigned pk2(float lo, float hi) { f32x2_t v = {lo, hi}; bf16x2_t b = __builtin_convertvector(v, bf16x2_t); return __builtin_bit_cast(unsigned, b); }
; __device__ __forceinline__ void rms_rows(const float* x, const float* gain, bf16_t* out, int nrows, int gw, int NGW, int lane) {
;     ...
;     for (int m = gw; m < nrows; m += NGW) {
;         const f32x4* xr = (const f32x4*)(x + (size_t)m * DM) + lane; f32x4 v[4]; float ss = 0.f;
; #pragma unroll
;         for (int j = 0; j < 4; ++j) { v[j] = xr[64 * j]; ss += (v[j].x * v[j].x + v[j].y * v[j].y) + (v[j].z * v[j].z + v[j].w * v[j].w); }
;         const float rstd = rsqrtf(wave_sum(ss, lane) * (1.f / DM) + opq(EPS));
;         u32x2* o = (u32x2*)(out + (size_t)m * DM) + lane;
; #pragma unroll
;         for (int j = 0; j < 4; ++j) { u32x2 w; w.x = pk2(v[j].x * rstd * gv[j].x, v[j].y * rstd * gv[j].y); w.y = pk2(v[j].z * rstd * gv[j].z, v[j].w * rstd * gv[j].w); o[64 * j] = w; }
;     }
.Lrmsp656_body:
	v_mov_b32_e32 v26, v60
	v_mov_b32_e32 v27, v61
	v_mov_b32_e32 v28, v62
	v_mov_b32_e32 v29, v63
	v_mov_b32_e32 v30, v64
	v_mov_b32_e32 v31, v65
	v_mov_b32_e32 v32, v66
	v_mov_b32_e32 v33, v67
	v_mov_b32_e32 v34, v68
	v_mov_b32_e32 v35, v69
	v_mov_b32_e32 v36, v70
	v_mov_b32_e32 v37, v71
	v_mov_b32_e32 v38, v72
	v_mov_b32_e32 v39, v73
	v_mov_b32_e32 v40, v74
	v_mov_b32_e32 v41, v75
	v_mov_b32_e32 v42, 0x358637bd
	s_add_i32 s4, s4, s78
	s_cmpk_gt_i32 s4, 0x1fff
	s_cbranch_scc1 .Lrmsp656_nopf
	v_lshl_add_u64 v[18:19], v[18:19], 0, s[10:11]
	global_load_dwordx4 v[60:63], v[18:19], off
	global_load_dwordx4 v[64:67], v[18:19], off offset:1024
	global_load_dwordx4 v[68:71], v[18:19], off offset:2048
	global_load_dwordx4 v[72:75], v[18:19], off offset:3072
.Lrmsp656_nopf:
	v_mul_f32_e32 v43, v27, v27
	v_mul_f32_e32 v44, v29, v29
	v_mul_f32_e32 v45, v31, v31
	v_mul_f32_e32 v46, v33, v33
	v_mul_f32_e32 v47, v35, v35
	v_mul_f32_e32 v48, v37, v37
	v_fmac_f32_e32 v43, v26, v26
	v_fmac_f32_e32 v44, v28, v28
	v_fmac_f32_e32 v45, v30, v30
	v_fmac_f32_e32 v46, v32, v32
	v_mul_f32_e32 v49, v39, v39
	v_mul_f32_e32 v50, v41, v41
	v_fmac_f32_e32 v47, v34, v34
	v_fmac_f32_e32 v48, v36, v36
	v_add_f32_e32 v43, v43, v44
	v_add_f32_e32 v44, v45, v46
	v_fmac_f32_e32 v49, v38, v38
	v_fmac_f32_e32 v50, v40, v40
	v_add_f32_e32 v45, v47, v48
	v_add_f32_e32 v43, v43, v44
	v_add_f32_e32 v46, v49, v50
	v_add_f32_e32 v43, v43, v45
	v_add_f32_e32 v43, v43, v46
	ds_bpermute_b32 v44, v0, v43
	s_waitcnt lgkmcnt(0)
	v_add_f32_e32 v43, v43, v44
	ds_bpermute_b32 v44, v22, v43
	s_waitcnt lgkmcnt(0)
	v_add_f32_e32 v43, v43, v44
	ds_bpermute_b32 v44, v23, v43
	s_waitcnt lgkmcnt(0)
	v_add_f32_e32 v43, v43, v44
	ds_bpermute_b32 v44, v24, v43
	s_waitcnt lgkmcnt(0)
	v_add_f32_e32 v43, v43, v44
	ds_bpermute_b32 v44, v25, v43
	s_waitcnt lgkmcnt(0)
	v_add_f32_e32 v43, v43, v44
	v_mov_b32_e32 v44, v43
	s_nop 1
	v_permlane32_swap_b32_e32 v43, v44
	v_add_f32_e32 v43, v43, v44
	v_fmac_f32_e32 v42, 0x3a800000, v43
	v_mul_f32_e32 v43, 0x4b800000, v42
	v_cmp_gt_f32_e32 vcc, s57, v42
	s_nop 1
	v_cndmask_b32_e32 v42, v42, v43, vcc
	v_rsq_f32_e32 v42, v42
	s_nop 0
	v_mul_f32_e32 v43, 0x45800000, v42
	v_cndmask_b32_e32 v42, v42, v43, vcc
	v_pk_mul_f32 v[26:27], v[26:27], v[42:43] op_sel_hi:[1,0]
	v_pk_mul_f32 v[28:29], v[28:29], v[42:43] op_sel_hi:[1,0]
	v_pk_mul_f32 v[30:31], v[30:31], v[42:43] op_sel_hi:[1,0]
	v_pk_mul_f32 v[32:33], v[32:33], v[42:43] op_sel_hi:[1,0]
	v_pk_mul_f32 v[34:35], v[34:35], v[42:43] op_sel_hi:[1,0]
	v_pk_mul_f32 v[36:37], v[36:37], v[42:43] op_sel_hi:[1,0]
	v_pk_mul_f32 v[38:39], v[38:39], v[42:43] op_sel_hi:[1,0]
	v_pk_mul_f32 v[40:41], v[40:41], v[42:43] op_sel_hi:[1,0]
	v_pk_mul_f32 v[26:27], v[14:15], v[26:27]
	v_pk_mul_f32 v[28:29], v[16:17], v[28:29]
	v_pk_mul_f32 v[30:31], v[10:11], v[30:31]
	v_pk_mul_f32 v[32:33], v[12:13], v[32:33]
	v_pk_mul_f32 v[34:35], v[6:7], v[34:35]
	v_pk_mul_f32 v[36:37], v[8:9], v[36:37]
	v_pk_mul_f32 v[38:39], v[2:3], v[38:39]
	v_pk_mul_f32 v[40:41], v[4:5], v[40:41]
	v_cvt_pk_bf16_f32 v26, v26, v27
	v_cvt_pk_bf16_f32 v27, v28, v29
	v_cvt_pk_bf16_f32 v28, v30, v31
	v_cvt_pk_bf16_f32 v29, v32, v33
	v_cvt_pk_bf16_f32 v30, v34, v35
	v_cvt_pk_bf16_f32 v31, v36, v37
	v_cvt_pk_bf16_f32 v32, v38, v39
	v_cvt_pk_bf16_f32 v33, v40, v41
	global_store_dwordx2 v[20:21], v[26:27], off
	global_store_dwordx2 v[20:21], v[28:29], off offset:512
	global_store_dwordx2 v[20:21], v[30:31], off offset:1024
	global_store_dwordx2 v[20:21], v[32:33], off offset:1536
	v_lshl_add_u64 v[20:21], v[20:21], 0, s[0:1]
	s_cmpk_gt_i32 s4, 0x1fff
	s_cbranch_scc0 .LBB0_656

;     static __device__ __forceinline__ float gv(unsigned long long gw, int i) { return __uint_as_float((unsigned)((gw >> (16 * i)) & 0xffffull) << 16); }
; __device__ __forceinline__ float opq(float v) { asm volatile("" : "+v"(v)); return v; }
; #define GET_IDS() unsigned zz_ = 0u; asm volatile("" : "+v"(zz_)); int lane = (int)__builtin_amdgcn_mbcnt_hi(~0u, __builtin_amdgcn_mbcnt_lo(~0u, zz_)); int wave = wave_id; asm volatile("" : "+s"(wave)); int tid = wave * 64 + lane; const int gw = bid * 8 + wave, gwb = wave * G + bid; (void)gw; (void)gwb; (void)lane
; __device__ __forceinline__ void rms_rows(const float* x, const float* gain, bf16_t* out, int nrows, int gw, int NGW, int lane) {
;     f32x4 gv[4];
; #pragma unroll
;     for (int j = 0; j < 4; ++j) gv[j] = *((const f32x4*)gain + lane + 64 * j);
;     for (int m = gw; m < nrows; m += NGW) {
;         const f32x4* xr = (const f32x4*)(x + (size_t)m * DM) + lane; f32x4 v[4]; float ss = 0.f;
; #pragma unroll
;         for (int j = 0; j < 4; ++j) { v[j] = xr[64 * j]; ss += (v[j].x * v[j].x + v[j].y * v[j].y) + (v[j].z * v[j].z + v[j].w * v[j].w); }
;         const float rstd = rsqrtf(wave_sum(ss, lane) * (1.f / DM) + opq(EPS));
;         u32x2* o = (u32x2*)(out + (size_t)m * DM) + lane;
; __global__ void __launch_bounds__(512, 2) mega_fwd(Args A_) {
;     ...
;             } else if (sub == 0) {
;                 GET_IDS();
;                 rms_rows(A.out() + (size_t)grp * TG * DM, A.in(I_MIXN) + L * DM, hbuf, TG, gw, NGW, lane);
.LBB0_968:
	s_andn2_b64 vcc, exec, s[2:3]
	s_cbranch_vccnz .LBB0_973
	v_readlane_b32 s0, v254, 38
	s_cmp_lg_u32 s0, 0
	s_cbranch_scc1 .LBB0_973
	v_mov_b32_e32 v0, v1
	v_readlane_b32 s0, v254, 5
	s_lshl_b32 s1, s79, 3
	s_add_i32 s2, s0, s1
	s_cmpk_gt_i32 s2, 0x1fff
	s_cbranch_scc1 .LBB0_973
	v_readlane_b32 s0, v254, 36
	v_readlane_b32 s1, v254, 37
	s_load_dwordx2 s[4:5], s[0:1], 0x20
	v_readlane_b32 s6, v254, 32
	v_readlane_b32 s7, v254, 33
	s_lshl_b32 s6, s6, 10
	v_mbcnt_lo_u32_b32 v0, -1, v0
	s_ashr_i32 s7, s6, 31
	s_lshl_b64 s[6:7], s[6:7], 2
	v_mbcnt_hi_u32_b32 v18, -1, v0
	s_waitcnt lgkmcnt(0)
	s_add_u32 s4, s4, s6
	v_ashrrev_i32_e32 v19, 31, v18
	s_addc_u32 s5, s5, s7
	v_lshlrev_b64 v[20:21], 4, v[18:19]
	v_lshl_add_u64 v[14:15], s[4:5], 0, v[20:21]
	global_load_dwordx4 v[2:5], v[14:15], off offset:3072
	global_load_dwordx4 v[6:9], v[14:15], off offset:2048
	global_load_dwordx4 v[10:13], v[14:15], off offset:1024
	s_nop 0
	global_load_dwordx4 v[14:17], v[14:15], off
	s_ashr_i32 s3, s2, 31
	s_lshl_b64 s[6:7], s[2:3], 11
	s_load_dwordx2 s[4:5], s[0:1], 0xd8
	s_add_u32 s6, s94, s6
	s_addc_u32 s7, s95, s7
	v_readlane_b32 s0, v254, 39
	v_lshlrev_b32_e32 v25, 2, v18
	v_lshl_add_u64 v[18:19], v[18:19], 3, s[6:7]
	s_lshl_b32 s0, s0, 25
	s_lshl_b64 s[6:7], s[2:3], 12
	s_add_u32 s0, s0, s6
	s_addc_u32 s1, 0, s7
	s_waitcnt lgkmcnt(0)
	s_add_u32 s4, s4, s0
	s_addc_u32 s5, s5, s1
	v_lshl_add_u64 v[20:21], s[4:5], 0, v[20:21]
	s_mov_b64 s[0:1], 0xc00
	v_lshl_add_u64 v[20:21], v[20:21], 0, s[0:1]
	v_readlane_b32 s0, v254, 30
	v_readlane_b32 s4, v254, 19
	v_xor_b32_e32 v0, 4, v25
	v_xor_b32_e32 v22, 8, v25
	v_xor_b32_e32 v23, 16, v25
	v_xor_b32_e32 v24, 32, v25
	v_xor_b32_e32 v25, 64, v25
	v_readlane_b32 s1, v254, 31
	v_readlane_b32 s5, v254, 20
	global_load_dwordx4 v[60:63], v[20:21], off offset:-3072
	global_load_dwordx4 v[64:67], v[20:21], off offset:-2048
	global_load_dwordx4 v[68:71], v[20:21], off offset:-1024
	global_load_dwordx4 v[72:75], v[20:21], off
	s_waitcnt vmcnt(0)
	s_branch .Lrmsp972_body

;     static __device__ __forceinline__ float gv(unsigned long long gw, int i) { return __uint_as_float((unsigned)((gw >> (16 * i)) & 0xffffull) << 16); }
; __device__ __forceinline__ float opq(float v) { asm volatile("" : "+v"(v)); return v; }
; __device__ __forceinline__ unsigned pk2(float lo, float hi) { f32x2_t v = {lo, hi}; bf16x2_t b = __builtin_convertvector(v, bf16x2_t); return __builtin_bit_cast(unsigned, b); }
; __device__ __forceinline__ void rms_rows(const float* x, const float* gain, bf16_t* out, int nrows, int gw, int NGW, int lane) {
;     ...
;     for (int m = gw; m < nrows; m += NGW) {
;         const f32x4* xr = (const f32x4*)(x + (size_t)m * DM) + lane; f32x4 v[4]; float ss = 0.f;
; #pragma unroll
;         for (int j = 0; j < 4; ++j) { v[j] = xr[64 * j]; ss += (v[j].x * v[j].x + v[j].y * v[j].y) + (v[j].z * v[j].z + v[j].w * v[j].w); }
;         const float rstd = rsqrtf(wave_sum(ss, lane) * (1.f / DM) + opq(EPS));
;         u32x2* o = (u32x2*)(out + (size_t)m * DM) + lane;
; #pragma unroll
;         for (int j = 0; j < 4; ++j) { u32x2 w; w.x = pk2(v[j].x * rstd * gv[j].x, v[j].y * rstd * gv[j].y); w.y = pk2(v[j].z * rstd * gv[j].z, v[j].w * rstd * gv[j].w); o[64 * j] = w; }
;     }
.Lrmsp972_body:
	v_mov_b32_e32 v26, v60
	v_mov_b32_e32 v27, v61
	v_mov_b32_e32 v28, v62
	v_mov_b32_e32 v29, v63
	v_mov_b32_e32 v30, v64
	v_mov_b32_e32 v31, v65
	v_mov_b32_e32 v32, v66
	v_mov_b32_e32 v33, v67
	v_mov_b32_e32 v34, v68
	v_mov_b32_e32 v35, v69
	v_mov_b32_e32 v36, v70
	v_mov_b32_e32 v37, v71
	v_mov_b32_e32 v38, v72
	v_mov_b32_e32 v39, v73
	v_mov_b32_e32 v40, v74
	v_mov_b32_e32 v41, v75
	v_mov_b32_e32 v42, 0x358637bd
	s_add_i32 s2, s2, s78
	s_cmpk_gt_i32 s2, 0x1fff
	s_cbranch_scc1 .Lrmsp972_nopf
	v_lshl_add_u64 v[20:21], v[20:21], 0, s[4:5]
	global_load_dwordx4 v[60:63], v[20:21], off offset:-3072
	global_load_dwordx4 v[64:67], v[20:21], off offset:-2048
	global_load_dwordx4 v[68:71], v[20:21], off offset:-1024
	global_load_dwordx4 v[72:75], v[20:21], off
.Lrmsp972_nopf:
	v_mul_f32_e32 v43, v27, v27
	v_mul_f32_e32 v44, v29, v29
	v_mul_f32_e32 v45, v31, v31
	v_mul_f32_e32 v46, v33, v33
	v_mul_f32_e32 v47, v35, v35
	v_mul_f32_e32 v48, v37, v37
	v_fmac_f32_e32 v43, v26, v26
	v_fmac_f32_e32 v44, v28, v28
	v_fmac_f32_e32 v45, v30, v30
	v_fmac_f32_e32 v46, v32, v32
	v_mul_f32_e32 v49, v39, v39
	v_mul_f32_e32 v50, v41, v41
	v_fmac_f32_e32 v47, v34, v34
	v_fmac_f32_e32 v48, v36, v36
	v_add_f32_e32 v43, v43, v44
	v_add_f32_e32 v44, v45, v46
	v_fmac_f32_e32 v49, v38, v38
	v_fmac_f32_e32 v50, v40, v40
	v_add_f32_e32 v45, v47, v48
	v_add_f32_e32 v43, v43, v44
	v_add_f32_e32 v46, v49, v50
	v_add_f32_e32 v43, v43, v45
	v_add_f32_e32 v43, v43, v46
	ds_bpermute_b32 v44, v0, v43
	s_waitcnt lgkmcnt(0)
	v_add_f32_e32 v43, v43, v44
	ds_bpermute_b32 v44, v22, v43
	s_waitcnt lgkmcnt(0)
	v_add_f32_e32 v43, v43, v44
	ds_bpermute_b32 v44, v23, v43
	s_waitcnt lgkmcnt(0)
	v_add_f32_e32 v43, v43, v44
	ds_bpermute_b32 v44, v24, v43
	s_waitcnt lgkmcnt(0)
	v_add_f32_e32 v43, v43, v44
	ds_bpermute_b32 v44, v25, v43
	s_waitcnt lgkmcnt(0)
	v_add_f32_e32 v43, v43, v44
	v_mov_b32_e32 v44, v43
	s_nop 1
	v_permlane32_swap_b32_e32 v43, v44
	v_add_f32_e32 v43, v43, v44
	v_fmac_f32_e32 v42, 0x3a800000, v43
	v_mul_f32_e32 v43, 0x4b800000, v42
	v_cmp_gt_f32_e32 vcc, s57, v42
	s_nop 1
	v_cndmask_b32_e32 v42, v42, v43, vcc
	v_rsq_f32_e32 v42, v42
	s_nop 0
	v_mul_f32_e32 v43, 0x45800000, v42
	v_cndmask_b32_e32 v42, v42, v43, vcc
	v_pk_mul_f32 v[26:27], v[26:27], v[42:43] op_sel_hi:[1,0]
	v_pk_mul_f32 v[28:29], v[28:29], v[42:43] op_sel_hi:[1,0]
	v_pk_mul_f32 v[30:31], v[30:31], v[42:43] op_sel_hi:[1,0]
	v_pk_mul_f32 v[32:33], v[32:33], v[42:43] op_sel_hi:[1,0]
	v_pk_mul_f32 v[34:35], v[34:35], v[42:43] op_sel_hi:[1,0]
	v_pk_mul_f32 v[36:37], v[36:37], v[42:43] op_sel_hi:[1,0]
	v_pk_mul_f32 v[38:39], v[38:39], v[42:43] op_sel_hi:[1,0]
	v_pk_mul_f32 v[40:41], v[40:41], v[42:43] op_sel_hi:[1,0]
	v_pk_mul_f32 v[26:27], v[14:15], v[26:27]
	v_pk_mul_f32 v[28:29], v[16:17], v[28:29]
	v_pk_mul_f32 v[30:31], v[10:11], v[30:31]
	v_pk_mul_f32 v[32:33], v[12:13], v[32:33]
	v_pk_mul_f32 v[34:35], v[6:7], v[34:35]
	v_pk_mul_f32 v[36:37], v[8:9], v[36:37]
	v_pk_mul_f32 v[38:39], v[2:3], v[38:39]
	v_pk_mul_f32 v[40:41], v[4:5], v[40:41]
	v_cvt_pk_bf16_f32 v26, v26, v27
	v_cvt_pk_bf16_f32 v27, v28, v29
	v_cvt_pk_bf16_f32 v28, v30, v31
	v_cvt_pk_bf16_f32 v29, v32, v33
	v_cvt_pk_bf16_f32 v30, v34, v35
	v_cvt_pk_bf16_f32 v31, v36, v37
	v_cvt_pk_bf16_f32 v32, v38, v39
	v_cvt_pk_bf16_f32 v33, v40, v41
	global_store_dwordx2 v[18:19], v[26:27], off
	global_store_dwordx2 v[18:19], v[28:29], off offset:512
	global_store_dwordx2 v[18:19], v[30:31], off offset:1024
	global_store_dwordx2 v[18:19], v[32:33], off offset:1536
	v_lshl_add_u64 v[18:19], v[18:19], 0, s[0:1]
	s_cmpk_gt_i32 s2, 0x1fff
	s_cbranch_scc0 .LBB0_972

;     static __device__ __forceinline__ float gv(unsigned long long gw, int i) { return __uint_as_float((unsigned)((gw >> (16 * i)) & 0xffffull) << 16); }
; #define LAS __attribute__((address_space(3)))
; __device__ __forceinline__ float opq(float v) { asm volatile("" : "+v"(v)); return v; }
; #define GET_IDS() unsigned zz_ = 0u; asm volatile("" : "+v"(zz_)); int lane = (int)__builtin_amdgcn_mbcnt_hi(~0u, __builtin_amdgcn_mbcnt_lo(~0u, zz_)); int wave = wave_id; asm volatile("" : "+s"(wave)); int tid = wave * 64 + lane; const int gw = bid * 8 + wave, gwb = wave * G + bid; (void)gw; (void)gwb; (void)lane
; __device__ __forceinline__ void rms_rows(const float* x, const float* gain, bf16_t* out, int nrows, int gw, int NGW, int lane) {
;     f32x4 gv[4];
; #pragma unroll
;     for (int j = 0; j < 4; ++j) gv[j] = *((const f32x4*)gain + lane + 64 * j);
;     for (int m = gw; m < nrows; m += NGW) {
;         const f32x4* xr = (const f32x4*)(x + (size_t)m * DM) + lane; f32x4 v[4]; float ss = 0.f;
; #pragma unroll
;         for (int j = 0; j < 4; ++j) { v[j] = xr[64 * j]; ss += (v[j].x * v[j].x + v[j].y * v[j].y) + (v[j].z * v[j].z + v[j].w * v[j].w); }
;         const float rstd = rsqrtf(wave_sum(ss, lane) * (1.f / DM) + opq(EPS));
;         u32x2* o = (u32x2*)(out + (size_t)m * DM) + lane;
; __global__ void __launch_bounds__(512, 2) mega_fwd(Args A_) {
;     ...
;             if (st == 0) {
;                 GET_IDS();
;                 if (L == 0) convert_weights(A, 0, 1, (LAS float*)(lds + wave * 16384), gwb, NGW, lane);
;                 if (L == 0) rope_tables(ws, bid * 512 + tid, G * 512);
;                 rms_rows(xin, A.in(I_F1N) + L * DM, hbuf, NTOK, gw, NGW, lane);
.LBB0_1016:
	s_lshl_b32 s0, s79, 3
	s_add_i32 s2, s12, s0
	s_cmpk_gt_i32 s2, 0x3fff
	s_cbranch_scc1 .LBB0_1019
	v_readlane_b32 s0, v254, 36
	v_readlane_b32 s1, v254, 37
	s_load_dwordx2 s[0:1], s[0:1], 0x8
	v_readlane_b32 s4, v254, 32
	v_readlane_b32 s5, v254, 33
	s_lshl_b32 s4, s4, 10
	s_ashr_i32 s5, s4, 31
	s_lshl_b64 s[4:5], s[4:5], 2
	v_ashrrev_i32_e32 v19, 31, v18
	s_waitcnt lgkmcnt(0)
	s_add_u32 s0, s0, s4
	s_addc_u32 s1, s1, s5
	v_lshlrev_b64 v[20:21], 4, v[18:19]
	v_lshl_add_u64 v[14:15], s[0:1], 0, v[20:21]
	global_load_dwordx4 v[2:5], v[14:15], off offset:3072
	global_load_dwordx4 v[6:9], v[14:15], off offset:2048
	global_load_dwordx4 v[10:13], v[14:15], off offset:1024
	s_nop 0
	global_load_dwordx4 v[14:17], v[14:15], off
	s_ashr_i32 s3, s2, 31
	s_lshl_b64 s[0:1], s[2:3], 11
	s_add_u32 s0, s94, s0
	s_addc_u32 s1, s95, s1
	v_lshlrev_b32_e32 v25, 2, v18
	v_lshl_add_u64 v[18:19], v[18:19], 3, s[0:1]
	s_lshl_b64 s[0:1], s[2:3], 12
	v_readlane_b32 s4, v254, 40
	v_readlane_b32 s5, v254, 41
	s_add_u32 s0, s4, s0
	s_addc_u32 s1, s5, s1
	v_lshl_add_u64 v[20:21], s[0:1], 0, v[20:21]
	s_mov_b64 s[0:1], 0xc00
	v_lshl_add_u64 v[20:21], v[20:21], 0, s[0:1]
	v_readlane_b32 s0, v254, 30
	v_readlane_b32 s4, v254, 19
	v_xor_b32_e32 v0, 4, v25
	v_xor_b32_e32 v22, 8, v25
	v_xor_b32_e32 v23, 16, v25
	v_xor_b32_e32 v24, 32, v25
	v_xor_b32_e32 v25, 64, v25
	v_readlane_b32 s1, v254, 31
	v_readlane_b32 s5, v254, 20
	global_load_dwordx4 v[60:63], v[20:21], off offset:-3072
	global_load_dwordx4 v[64:67], v[20:21], off offset:-2048
	global_load_dwordx4 v[68:71], v[20:21], off offset:-1024
	global_load_dwordx4 v[72:75], v[20:21], off
	s_waitcnt vmcnt(0)
	s_branch .Lrmsp1018_body

;     static __device__ __forceinline__ float gv(unsigned long long gw, int i) { return __uint_as_float((unsigned)((gw >> (16 * i)) & 0xffffull) << 16); }
; __device__ __forceinline__ float opq(float v) { asm volatile("" : "+v"(v)); return v; }
; __device__ __forceinline__ unsigned pk2(float lo, float hi) { f32x2_t v = {lo, hi}; bf16x2_t b = __builtin_convertvector(v, bf16x2_t); return __builtin_bit_cast(unsigned, b); }
; __device__ __forceinline__ void rms_rows(const float* x, const float* gain, bf16_t* out, int nrows, int gw, int NGW, int lane) {
;     ...
;     for (int m = gw; m < nrows; m += NGW) {
;         const f32x4* xr = (const f32x4*)(x + (size_t)m * DM) + lane; f32x4 v[4]; float ss = 0.f;
; #pragma unroll
;         for (int j = 0; j < 4; ++j) { v[j] = xr[64 * j]; ss += (v[j].x * v[j].x + v[j].y * v[j].y) + (v[j].z * v[j].z + v[j].w * v[j].w); }
;         const float rstd = rsqrtf(wave_sum(ss, lane) * (1.f / DM) + opq(EPS));
;         u32x2* o = (u32x2*)(out + (size_t)m * DM) + lane;
; #pragma unroll
;         for (int j = 0; j < 4; ++j) { u32x2 w; w.x = pk2(v[j].x * rstd * gv[j].x, v[j].y * rstd * gv[j].y); w.y = pk2(v[j].z * rstd * gv[j].z, v[j].w * rstd * gv[j].w); o[64 * j] = w; }
;     }
.Lrmsp1018_body:
	v_mov_b32_e32 v26, v60
	v_mov_b32_e32 v27, v61
	v_mov_b32_e32 v28, v62
	v_mov_b32_e32 v29, v63
	v_mov_b32_e32 v30, v64
	v_mov_b32_e32 v31, v65
	v_mov_b32_e32 v32, v66
	v_mov_b32_e32 v33, v67
	v_mov_b32_e32 v34, v68
	v_mov_b32_e32 v35, v69
	v_mov_b32_e32 v36, v70
	v_mov_b32_e32 v37, v71
	v_mov_b32_e32 v38, v72
	v_mov_b32_e32 v39, v73
	v_mov_b32_e32 v40, v74
	v_mov_b32_e32 v41, v75
	v_mov_b32_e32 v42, 0x358637bd
	s_add_i32 s2, s2, s78
	s_cmpk_gt_i32 s2, 0x3fff
	s_cbranch_scc1 .Lrmsp1018_nopf
	v_lshl_add_u64 v[20:21], v[20:21], 0, s[4:5]
	global_load_dwordx4 v[60:63], v[20:21], off offset:-3072
	global_load_dwordx4 v[64:67], v[20:21], off offset:-2048
	global_load_dwordx4 v[68:71], v[20:21], off offset:-1024
	global_load_dwordx4 v[72:75], v[20:21], off
.Lrmsp1018_nopf:
	v_mul_f32_e32 v43, v27, v27
	v_mul_f32_e32 v44, v29, v29
	v_mul_f32_e32 v45, v31, v31
	v_mul_f32_e32 v46, v33, v33
	v_mul_f32_e32 v47, v35, v35
	v_mul_f32_e32 v48, v37, v37
	v_fmac_f32_e32 v43, v26, v26
	v_fmac_f32_e32 v44, v28, v28
	v_fmac_f32_e32 v45, v30, v30
	v_fmac_f32_e32 v46, v32, v32
	v_mul_f32_e32 v49, v39, v39
	v_mul_f32_e32 v50, v41, v41
	v_fmac_f32_e32 v47, v34, v34
	v_fmac_f32_e32 v48, v36, v36
	v_add_f32_e32 v43, v43, v44
	v_add_f32_e32 v44, v45, v46
	v_fmac_f32_e32 v49, v38, v38
	v_fmac_f32_e32 v50, v40, v40
	v_add_f32_e32 v45, v47, v48
	v_add_f32_e32 v43, v43, v44
	v_add_f32_e32 v46, v49, v50
	v_add_f32_e32 v43, v43, v45
	v_add_f32_e32 v43, v43, v46
	ds_bpermute_b32 v44, v0, v43
	s_waitcnt lgkmcnt(0)
	v_add_f32_e32 v43, v43, v44
	ds_bpermute_b32 v44, v22, v43
	s_waitcnt lgkmcnt(0)
	v_add_f32_e32 v43, v43, v44
	ds_bpermute_b32 v44, v23, v43
	s_waitcnt lgkmcnt(0)
	v_add_f32_e32 v43, v43, v44
	ds_bpermute_b32 v44, v24, v43
	s_waitcnt lgkmcnt(0)
	v_add_f32_e32 v43, v43, v44
	ds_bpermute_b32 v44, v25, v43
	s_waitcnt lgkmcnt(0)
	v_add_f32_e32 v43, v43, v44
	v_mov_b32_e32 v44, v43
	s_nop 1
	v_permlane32_swap_b32_e32 v43, v44
	v_add_f32_e32 v43, v43, v44
	v_fmac_f32_e32 v42, 0x3a800000, v43
	v_mul_f32_e32 v43, 0x4b800000, v42
	v_cmp_gt_f32_e32 vcc, s57, v42
	s_nop 1
	v_cndmask_b32_e32 v42, v42, v43, vcc
	v_rsq_f32_e32 v42, v42
	s_nop 0
	v_mul_f32_e32 v43, 0x45800000, v42
	v_cndmask_b32_e32 v42, v42, v43, vcc
	v_pk_mul_f32 v[26:27], v[26:27], v[42:43] op_sel_hi:[1,0]
	v_pk_mul_f32 v[28:29], v[28:29], v[42:43] op_sel_hi:[1,0]
	v_pk_mul_f32 v[30:31], v[30:31], v[42:43] op_sel_hi:[1,0]
	v_pk_mul_f32 v[32:33], v[32:33], v[42:43] op_sel_hi:[1,0]
	v_pk_mul_f32 v[34:35], v[34:35], v[42:43] op_sel_hi:[1,0]
	v_pk_mul_f32 v[36:37], v[36:37], v[42:43] op_sel_hi:[1,0]
	v_pk_mul_f32 v[38:39], v[38:39], v[42:43] op_sel_hi:[1,0]
	v_pk_mul_f32 v[40:41], v[40:41], v[42:43] op_sel_hi:[1,0]
	v_pk_mul_f32 v[26:27], v[14:15], v[26:27]
	v_pk_mul_f32 v[28:29], v[16:17], v[28:29]
	v_pk_mul_f32 v[30:31], v[10:11], v[30:31]
	v_pk_mul_f32 v[32:33], v[12:13], v[32:33]
	v_pk_mul_f32 v[34:35], v[6:7], v[34:35]
	v_pk_mul_f32 v[36:37], v[8:9], v[36:37]
	v_pk_mul_f32 v[38:39], v[2:3], v[38:39]
	v_pk_mul_f32 v[40:41], v[4:5], v[40:41]
	v_cvt_pk_bf16_f32 v26, v26, v27
	v_cvt_pk_bf16_f32 v27, v28, v29
	v_cvt_pk_bf16_f32 v28, v30, v31
	v_cvt_pk_bf16_f32 v29, v32, v33
	v_cvt_pk_bf16_f32 v30, v34, v35
	v_cvt_pk_bf16_f32 v31, v36, v37
	v_cvt_pk_bf16_f32 v32, v38, v39
	v_cvt_pk_bf16_f32 v33, v40, v41
	global_store_dwordx2 v[18:19], v[26:27], off
	global_store_dwordx2 v[18:19], v[28:29], off offset:512
	global_store_dwordx2 v[18:19], v[30:31], off offset:1024
	global_store_dwordx2 v[18:19], v[32:33], off offset:1536
	v_lshl_add_u64 v[18:19], v[18:19], 0, s[0:1]
	s_cmpk_gt_i32 s2, 0x3fff
	s_cbranch_scc0 .LBB0_1018
